# prep2: XCD-local id map (16 heads of one row tile on one XCD; LoRA-down rows shared in L2)
# speedup vs baseline: 1.0078x; 1.0078x over previous
.LBB0_539:
	s_lshr_b32 s0, s87, 7
	s_lshl_b32 s0, s0, 3
	s_and_b32 s10, s87, 7
	s_or_b32 s0, s0, s10
	s_lshl_b32 s0, s0, 7
	v_add_u32_e32 v99, s0, v151
	v_or_b32_e32 v0, v99, v149
	v_ashrrev_i32_e32 v1, 31, v0
	v_lshlrev_b64 v[8:9], 7, v[0:1]
	v_lshl_add_u64 v[146:147], v[88:89], 0, v[8:9]
	global_load_dwordx4 v[0:3], v[146:147], off
	s_bfe_u32 s10, s87, 0x40003
	v_lshl_or_b32 v68, s10, 13, v200
	s_waitcnt lgkmcnt(0)
	v_lshl_add_u64 v[4:5], v[72:73], 0, v[68:69]
	global_load_dwordx4 v[4:7], v[4:5], off
	v_lshl_add_u64 v[160:161], v[90:91], 0, v[8:9]
	global_load_dwordx4 v[8:11], v[160:161], off
	v_mov_b32_e32 v163, v69
	v_or_b32_e32 v162, 0x1000, v68
	v_lshl_add_u64 v[16:17], v[72:73], 0, v[162:163]
	v_lshl_add_u64 v[12:13], v[74:75], 0, v[68:69]
	global_load_dwordx4 v[16:19], v[16:17], off
	v_lshl_add_u64 v[20:21], v[74:75], 0, v[162:163]
	global_load_dwordx4 v[12:15], v[12:13], off
	s_nop 0
	global_load_dwordx4 v[64:67], v[20:21], off
	global_load_dwordx4 v[100:103], v[146:147], off offset:32
	v_lshl_add_u64 v[164:165], s[68:69], 0, v[68:69]
	v_lshl_add_u64 v[20:21], v[164:165], 0, v[92:93]
	v_lshl_add_u64 v[166:167], s[4:5], 0, v[68:69]
	global_load_dwordx4 v[104:107], v[20:21], off
	global_load_dwordx4 v[108:111], v[160:161], off offset:32
	v_lshl_add_u64 v[20:21], v[166:167], 0, v[92:93]
	global_load_dwordx4 v[112:115], v[20:21], off
	v_lshl_add_u64 v[20:21], v[76:77], 0, v[162:163]
	global_load_dwordx4 v[116:119], v[20:21], off
	v_lshl_add_u64 v[20:21], v[78:79], 0, v[162:163]
	global_load_dwordx4 v[120:123], v[20:21], off
	global_load_dwordx4 v[124:127], v[146:147], off offset:64
	v_lshl_add_u64 v[20:21], v[164:165], 0, v[94:95]
	global_load_dwordx4 v[128:131], v[20:21], off
	global_load_dwordx4 v[132:135], v[160:161], off offset:64
	v_lshl_add_u64 v[152:153], v[82:83], 0, v[162:163]
	v_lshl_or_b32 v211, s10, 6, v149
	v_lshlrev_b32_e32 v145, 2, v211
	s_lshl_b32 s70, s10, 7
	s_waitcnt vmcnt(13)
	v_mfma_f32_32x32x16_bf16 v[48:63], v[0:3], v[4:7], 0
	v_lshl_add_u64 v[4:5], v[166:167], 0, v[94:95]
	global_load_dwordx4 v[136:139], v[4:5], off
	v_lshl_add_u64 v[4:5], v[80:81], 0, v[162:163]
	global_load_dwordx4 v[140:143], v[4:5], off
	s_nop 0
	global_load_dwordx4 v[152:155], v[152:153], off
	s_nop 0
	global_load_dwordx4 v[156:159], v[146:147], off offset:96
	v_lshl_add_u64 v[146:147], v[166:167], 0, v[96:97]
	s_waitcnt vmcnt(15)
	v_mfma_f32_32x32x16_bf16 v[16:31], v[0:3], v[16:19], 0
	s_waitcnt vmcnt(14)
	v_mfma_f32_32x32x16_bf16 v[32:47], v[8:11], v[12:15], 0
	s_waitcnt vmcnt(13)
	v_mfma_f32_32x32x16_bf16 v[0:15], v[8:11], v[64:67], 0
	v_lshl_add_u64 v[64:65], v[164:165], 0, v[96:97]
	s_waitcnt vmcnt(11)
	v_mfma_f32_32x32x16_bf16 v[48:63], v[100:103], v[104:107], v[48:63]
	global_load_dwordx4 v[104:107], v[64:65], off
	s_nop 0
	global_load_dwordx4 v[64:67], v[160:161], off offset:96
	s_waitcnt vmcnt(10)
	v_mfma_f32_32x32x16_bf16 v[16:31], v[100:103], v[116:119], v[16:31]
	v_lshl_add_u64 v[100:101], v[86:87], 0, v[162:163]
	v_or_b32_e32 v102, v99, v198
	v_or_b32_e32 v170, 1, v102
	v_or_b32_e32 v160, 2, v102
	v_ashrrev_i32_e32 v171, 31, v170
	v_ashrrev_i32_e32 v161, 31, v160
	v_ashrrev_i32_e32 v103, 31, v102
	v_mfma_f32_32x32x16_bf16 v[32:47], v[108:111], v[112:115], v[32:47]
	global_load_dwordx4 v[112:115], v[146:147], off
	v_lshlrev_b64 v[180:181], 11, v[102:103]
	v_lshl_or_b32 v190, v211, 1, v180
	v_mov_b32_e32 v191, v181
	v_mov_b32_e32 v183, v181
	v_or_b32_e32 v182, 64, v190
	v_lshl_add_u64 v[192:193], s[26:27], 0, v[190:191]
	s_waitcnt vmcnt(10)
	v_mfma_f32_32x32x16_bf16 v[0:15], v[108:111], v[120:123], v[0:15]
	global_load_dwordx4 v[108:111], v[100:101], off
	v_lshl_add_u64 v[146:147], v[84:85], 0, v[162:163]
	global_load_dwordx4 v[116:119], v[146:147], off
	v_lshlrev_b64 v[100:101], 10, v[170:171]
	v_lshlrev_b64 v[120:121], 10, v[160:161]
	v_or_b32_e32 v100, v100, v211
	v_or_b32_e32 v120, v120, v211
	v_lshlrev_b64 v[176:177], 1, v[100:101]
	v_or_b32_e32 v100, 32, v100
	v_lshlrev_b64 v[166:167], 1, v[120:121]
	v_or_b32_e32 v120, 32, v120
	v_lshl_add_u64 v[122:123], s[30:31], 0, v[190:191]
	v_lshlrev_b64 v[172:173], 1, v[100:101]
	v_lshlrev_b64 v[162:163], 1, v[120:121]
	s_waitcnt vmcnt(10)
	v_mfma_f32_32x32x16_bf16 v[48:63], v[124:127], v[128:131], v[48:63]
	v_lshl_add_u64 v[184:185], s[26:27], 0, v[182:183]
	v_lshl_add_u64 v[100:101], s[30:31], 0, v[166:167]
	v_lshl_add_u64 v[120:121], s[30:31], 0, v[172:173]
	v_lshl_add_u64 v[128:129], s[30:31], 0, v[162:163]
	v_lshl_add_u64 v[178:179], s[26:27], 0, v[176:177]
	v_lshl_add_u64 v[174:175], s[26:27], 0, v[172:173]
	v_lshl_add_u64 v[168:169], s[26:27], 0, v[166:167]
	v_lshl_add_u64 v[164:165], s[26:27], 0, v[162:163]
	s_waitcnt vmcnt(8)
	v_mfma_f32_32x32x16_bf16 v[32:47], v[132:135], v[136:139], v[32:47]
	s_waitcnt vmcnt(7)
	v_mfma_f32_32x32x16_bf16 v[16:31], v[124:127], v[140:143], v[16:31]
	v_lshl_add_u64 v[124:125], s[30:31], 0, v[182:183]
	v_lshl_add_u64 v[126:127], s[30:31], 0, v[176:177]
	global_load_ushort v197, v[122:123], off
	global_load_ushort v238, v[124:125], off
	global_load_ushort v237, v[126:127], off
	global_load_ushort v234, v[120:121], off
	global_load_ushort v233, v[100:101], off
	global_load_ushort v230, v[128:129], off
	global_load_ushort v99, v[184:185], off
	global_load_ushort v188, v[192:193], off
	global_load_dword v210, v145, s[24:25]
	global_load_dword v209, v145, s[28:29]
	global_load_dword v100, v145, s[36:37]
	global_load_dword v208, v145, s[38:39]
	global_load_dword v68, v145, s[40:41]
	global_load_dword v101, v145, s[36:37] offset:128
	global_load_dword v207, v145, s[24:25] offset:128
	global_load_dword v206, v145, s[28:29] offset:128
	global_load_dword v205, v145, s[38:39] offset:128
	global_load_dword v204, v145, s[40:41] offset:128
	v_or_b32_e32 v142, 3, v102
	v_ashrrev_i32_e32 v143, 31, v142
	v_or_b32_e32 v122, 9, v102
	s_waitcnt vmcnt(24)
	v_mfma_f32_32x32x16_bf16 v[0:15], v[132:135], v[152:155], v[0:15]
	v_or_b32_e32 v132, 8, v102
	v_ashrrev_i32_e32 v133, 31, v132
	v_ashrrev_i32_e32 v123, 31, v122
	s_waitcnt vmcnt(22)
	v_mfma_f32_32x32x16_bf16 v[48:63], v[156:159], v[104:107], v[48:63]
	v_lshlrev_b64 v[104:105], 10, v[142:143]
	v_or_b32_e32 v104, v104, v211
	s_waitcnt vmcnt(9)
	s_nop 8
	v_add_f32_e32 v48, v48, v210
	v_mfma_f32_32x32x16_bf16 v[32:47], v[64:67], v[112:115], v[32:47]
	v_or_b32_e32 v112, 10, v102
	v_ashrrev_i32_e32 v113, 31, v112
	v_lshlrev_b64 v[114:115], 10, v[112:113]
	v_or_b32_e32 v114, v114, v211
	v_max_f32_e64 v252, -v48, 0
	s_waitcnt vmcnt(8)
	s_nop 5
	v_add_f32_e32 v32, v32, v209
	v_mfma_f32_32x32x16_bf16 v[16:31], v[156:159], v[116:119], v[16:31]
	v_lshlrev_b64 v[156:157], 1, v[104:105]
	v_or_b32_e32 v104, 32, v104
	v_lshlrev_b64 v[152:153], 1, v[104:105]
	v_lshlrev_b64 v[104:105], 10, v[132:133]
	v_or_b32_e32 v104, v104, v211
	v_lshlrev_b64 v[118:119], 1, v[114:115]
	v_or_b32_e32 v114, 32, v114
	v_mfma_f32_32x32x16_bf16 v[0:15], v[64:67], v[108:111], v[0:15]
	v_lshlrev_b64 v[108:109], 10, v[122:123]
	v_or_b32_e32 v108, v108, v211
	v_lshlrev_b64 v[138:139], 1, v[104:105]
	v_or_b32_e32 v104, 32, v104
	v_lshlrev_b64 v[128:129], 1, v[108:109]
	v_or_b32_e32 v108, 32, v108
	v_lshlrev_b64 v[114:115], 1, v[114:115]
	v_lshl_add_u64 v[64:65], s[30:31], 0, v[156:157]
	v_lshlrev_b64 v[134:135], 1, v[104:105]
	v_lshlrev_b64 v[124:125], 1, v[108:109]
	v_lshl_add_u64 v[186:187], s[30:31], 0, v[114:115]
	v_lshl_add_u64 v[158:159], s[26:27], 0, v[156:157]
	v_lshl_add_u64 v[154:155], s[26:27], 0, v[152:153]
	v_lshl_add_u64 v[66:67], s[30:31], 0, v[152:153]
	v_lshl_add_u64 v[140:141], s[26:27], 0, v[138:139]
	v_lshl_add_u64 v[106:107], s[30:31], 0, v[138:139]
	v_lshl_add_u64 v[136:137], s[26:27], 0, v[134:135]
	global_load_ushort v239, v[178:179], off
	global_load_ushort v240, v[174:175], off
	global_load_ushort v235, v[168:169], off
	global_load_ushort v236, v[164:165], off
	global_load_ushort v231, v[158:159], off
	global_load_ushort v232, v[154:155], off
	global_load_ushort v226, v[140:141], off
	global_load_ushort v227, v[136:137], off
	v_lshl_add_u64 v[104:105], s[30:31], 0, v[134:135]
	v_lshl_add_u64 v[110:111], s[30:31], 0, v[128:129]
	v_lshl_add_u64 v[108:109], s[30:31], 0, v[124:125]
	v_lshl_add_u64 v[146:147], s[30:31], 0, v[118:119]
	global_load_ushort v229, v[64:65], off
	global_load_ushort v228, v[66:67], off
	global_load_ushort v225, v[106:107], off
	global_load_ushort v224, v[104:105], off
	global_load_ushort v221, v[110:111], off
	global_load_ushort v220, v[108:109], off
	global_load_ushort v217, v[146:147], off
	global_load_ushort v216, v[186:187], off
	v_lshlrev_b32_e32 v186, 16, v188
	v_lshlrev_b32_e32 v187, 16, v99
	s_waitcnt vmcnt(20)
	v_pk_mul_f32 v[188:189], v[100:101], v[186:187]
	v_or_b32_e32 v66, 11, v102
	v_pk_mul_f32 v[104:105], v[188:189], v[188:189]
	v_ashrrev_i32_e32 v67, 31, v66
	v_add_f32_e32 v99, v104, v105
	v_lshlrev_b64 v[64:65], 10, v[66:67]
	v_or_b32_e32 v64, v64, v211
	v_add_f32_dpp v99, v99, v99 quad_perm:[1,0,3,2] row_mask:0xf bank_mask:0xf bound_ctrl:1
	v_lshlrev_b64 v[108:109], 1, v[64:65]
	v_or_b32_e32 v64, 32, v64
	v_add_f32_dpp v99, v99, v99 quad_perm:[2,3,0,1] row_mask:0xf bank_mask:0xf bound_ctrl:1
	v_lshlrev_b64 v[104:105], 1, v[64:65]
	v_lshl_add_u64 v[130:131], s[26:27], 0, v[128:129]
	v_add_f32_dpp v99, v99, v99 row_half_mirror row_mask:0xf bank_mask:0xf bound_ctrl:1
	v_lshl_add_u64 v[146:147], s[30:31], 0, v[108:109]
	v_lshl_add_u64 v[126:127], s[26:27], 0, v[124:125]
	v_add_f32_dpp v99, v99, v99 row_mirror row_mask:0xf bank_mask:0xf bound_ctrl:1
	ds_bpermute_b32 v145, v199, v99
	v_lshl_add_u64 v[120:121], s[26:27], 0, v[118:119]
	v_lshl_add_u64 v[116:117], s[26:27], 0, v[114:115]
	v_lshl_add_u64 v[110:111], s[26:27], 0, v[108:109]
	v_lshl_add_u64 v[106:107], s[26:27], 0, v[104:105]
	s_waitcnt lgkmcnt(0)
	v_add_f32_e32 v64, v99, v145
	v_mul_f32_e32 v65, 0x4f800000, v64
	v_cmp_gt_f32_e32 vcc, s75, v64
	global_load_ushort v222, v[130:131], off
	global_load_ushort v223, v[126:127], off
	global_load_ushort v218, v[120:121], off
	global_load_ushort v219, v[116:117], off
	global_load_ushort v214, v[110:111], off
	global_load_ushort v215, v[106:107], off
	v_cndmask_b32_e32 v64, v64, v65, vcc
	v_sqrt_f32_e32 v65, v64
	s_waitcnt vmcnt(25)
	v_add_f32_e32 v16, v16, v207
	s_waitcnt vmcnt(24)
	v_add_f32_e32 v0, v0, v206
	v_add_u32_e32 v99, -1, v65
	v_fma_f32 v145, -v99, v65, v64
	v_cmp_ge_f32_e64 s[0:1], 0, v145
	v_add_u32_e32 v145, 1, v65
	s_nop 0
	v_cndmask_b32_e64 v99, v65, v99, s[0:1]
	v_fma_f32 v65, -v145, v65, v64
	v_cmp_lt_f32_e64 s[0:1], 0, v65
	s_nop 1
	v_cndmask_b32_e64 v65, v99, v145, s[0:1]
	v_mul_f32_e32 v99, 0x37800000, v65
	v_cndmask_b32_e32 v65, v65, v99, vcc
	v_cmp_class_f32_e32 vcc, v64, v201
	s_nop 1
	v_cndmask_b32_e32 v64, v65, v64, vcc
	v_max_f32_e32 v145, 0x2b8cbccc, v64
	v_lshl_add_u64 v[64:65], s[30:31], 0, v[104:105]
	global_load_ushort v213, v[146:147], off
	global_load_ushort v212, v[64:65], off
	s_nop 1
	v_mul_f32_e64 v48, |v48|, s76
	v_exp_f32_e32 v48, v48
	v_lshl_add_u64 v[194:195], s[54:55], 0, v[190:191]
	s_nop 0
	v_add_f32_e32 v64, 1.0, v48
	v_log_f32_e32 v64, v64
	s_nop 0
	v_mul_f32_e32 v48, 0x3f317218, v64
	v_add_f32_e32 v48, v252, v48
	v_sub_f32_e32 v48, -0.5, v48
	v_rcp_f32_e32 v145, v145
	s_nop 1
	v_mul_f32_e32 v32, 0xbfb8aa3b, v32
	v_exp_f32_e32 v32, v32
	s_nop 0
	v_add_f32_e32 v32, 1.0, v32
	s_lshl_b32 s0, s10, 3
	s_add_u32 s72, s97, s0
	s_addc_u32 s73, s46, 0
	s_nop 0
	v_mul_f32_e32 v48, 0x3fb8aa3b, v48
	v_exp_f32_e32 v48, v48
	v_rcp_f32_e32 v32, v32
	s_nop 0
	v_add_f32_e32 v65, -1.0, v32
	v_fma_f32 v65, v208, v65, 1.0
	v_mul_f32_e32 v64, v188, v145
	v_mul_f32_e32 v65, v65, v186
	v_cvt_pk_bf16_f32 v48, v48, 0
	v_cvt_pk_bf16_f32 v99, v65, 0
	v_cvt_pk_bf16_f32 v186, v64, 0
	v_mul_f32_e32 v32, v32, v64
	v_lshl_add_u64 v[64:65], s[20:21], 0, v[190:191]
	global_store_short v[194:195], v48, off
	global_store_short v[192:193], v99, off
	global_store_short v[64:65], v186, off
	v_lshl_add_u64 v[64:65], s[18:19], 0, v[190:191]
	v_lshlrev_b32_e32 v191, 16, v99
	v_cvt_pk_bf16_f32 v32, v32, 0
	v_lshlrev_b32_e32 v48, 16, v48
	v_mul_f32_e64 v99, |v16|, s76
	v_exp_f32_e32 v99, v99
	global_store_short v[64:65], v32, off
	v_lshlrev_b32_e32 v190, 16, v197
	v_mov_b32_e32 v64, v99
	v_max_f32_e64 v16, -v16, 0
	v_lshlrev_b32_e32 v32, 16, v32
	v_mov_b32_e32 v241, v64
	v_fma_f32 v32, v32, v190, 0
	v_lshlrev_b32_e32 v186, 16, v186
	v_mov_b32_e32 v99, v190
	v_pk_mul_f32 v[242:243], v[98:99], v[190:191]
	v_mov_b32_e32 v242, v191
	v_mov_b32_e32 v191, v68
	v_lshl_add_u64 v[64:65], v[70:71], 0, s[70:71]
	v_lshl_add_u64 v[180:181], v[64:65], 0, v[180:181]
	v_add_f32_e32 v146, 1.0, v241
	v_log_f32_e32 v146, v146
	s_nop 0
	v_mul_f32_e32 v146, 0x3f317218, v146
	v_add_f32_e32 v16, v16, v146
	v_sub_f32_e32 v16, -0.5, v16
	s_nop 1
	v_mul_f32_e32 v48, 0xbfb8aa3b, v48
	v_exp_f32_e32 v48, v48
	s_nop 1
	v_mul_f32_e32 v0, 0xbfb8aa3b, v0
	v_exp_f32_e32 v0, v0
	s_nop 0
	v_add_f32_e32 v0, 1.0, v0
	v_div_scale_f32 v146, s[0:1], v0, v0, 1.0
	s_nop 1
	v_mul_f32_e32 v16, 0x3fb8aa3b, v16
	v_exp_f32_e32 v16, v16
	v_rcp_f32_e32 v0, v0
	v_mul_f32_e32 v99, v189, v145
	v_add_f32_e32 v145, -1.0, v0
	s_waitcnt vmcnt(29)
	v_fma_f32 v145, v205, v145, 1.0
	v_mul_f32_e32 v145, v145, v187
	v_cvt_pk_bf16_f32 v16, v16, 0
	v_cvt_pk_bf16_f32 v145, v145, 0
	v_cvt_pk_bf16_f32 v187, v99, 0
	v_mul_f32_e32 v0, v0, v99
	global_store_short v[194:195], v16, off offset:64
	global_store_short v[184:185], v145, off
	v_lshl_add_u64 v[146:147], s[20:21], 0, v[182:183]
	v_lshlrev_b32_e32 v16, 16, v16
	v_cvt_pk_bf16_f32 v0, v0, 0
	global_store_short v[146:147], v187, off
	v_lshl_add_u64 v[146:147], s[18:19], 0, v[182:183]
	global_store_short v[146:147], v0, off
	v_lshlrev_b32_e32 v147, 16, v145
	v_mul_f32_e32 v145, 0xbfb8aa3b, v16
	v_exp_f32_e32 v145, v145
	v_lshlrev_b32_e32 v146, 16, v238
	v_mov_b32_e32 v99, v146
	v_lshlrev_b32_e32 v0, 16, v0
	v_pk_mul_f32 v[182:183], v[98:99], v[146:147]
	v_fmac_f32_e32 v32, v0, v146
	v_mov_b32_e32 v0, v145
	v_pk_fma_f32 v[184:185], v[242:243], v[190:191], 0 op_sel_hi:[1,1,0]
	v_mov_b32_e32 v182, v147
	s_waitcnt vmcnt(32)
	v_mov_b32_e32 v147, v204
	v_pk_fma_f32 v[182:183], v[182:183], v[146:147], v[184:185]
	v_add_f32_dpp v32, v32, v32 quad_perm:[1,0,3,2] row_mask:0xf bank_mask:0xf bound_ctrl:1
	s_nop 0
	v_mov_b32_dpp v184, v182 quad_perm:[1,0,3,2] row_mask:0xf bank_mask:0xf bound_ctrl:1
	v_mov_b32_dpp v185, v183 quad_perm:[1,0,3,2] row_mask:0xf bank_mask:0xf bound_ctrl:1
	v_add_f32_dpp v32, v32, v32 quad_perm:[2,3,0,1] row_mask:0xf bank_mask:0xf bound_ctrl:1
	v_pk_add_f32 v[182:183], v[182:183], v[184:185]
	s_nop 0
	v_add_f32_dpp v32, v32, v32 row_half_mirror row_mask:0xf bank_mask:0xf bound_ctrl:1
	v_mov_b32_dpp v184, v182 quad_perm:[2,3,0,1] row_mask:0xf bank_mask:0xf bound_ctrl:1
	v_mov_b32_dpp v185, v183 quad_perm:[2,3,0,1] row_mask:0xf bank_mask:0xf bound_ctrl:1
	v_add_f32_dpp v32, v32, v32 row_mirror row_mask:0xf bank_mask:0xf bound_ctrl:1
	v_pk_add_f32 v[182:183], v[182:183], v[184:185]
	ds_bpermute_b32 v99, v199, v32
	s_nop 0
	v_mov_b32_dpp v184, v182 row_half_mirror row_mask:0xf bank_mask:0xf bound_ctrl:1
	v_mov_b32_dpp v185, v183 row_half_mirror row_mask:0xf bank_mask:0xf bound_ctrl:1
	v_pk_add_f32 v[182:183], v[182:183], v[184:185]
	v_lshlrev_b32_e32 v16, 16, v187
	s_waitcnt lgkmcnt(0)
	v_add_f32_e32 v32, v32, v99
	v_mov_b32_dpp v184, v182 row_mirror row_mask:0xf bank_mask:0xf bound_ctrl:1
	v_mov_b32_dpp v185, v183 row_mirror row_mask:0xf bank_mask:0xf bound_ctrl:1
	v_pk_add_f32 v[182:183], v[182:183], v[184:185]
	ds_bpermute_b32 v184, v199, v182
	ds_bpermute_b32 v185, v199, v183
	v_mul_f32_e32 v99, v32, v186
	v_mul_f32_e32 v16, v32, v16
	v_fma_f32 v48, v48, v190, -v99
	v_fma_f32 v0, v0, v146, -v16
	v_cvt_pk_bf16_f32 v48, v48, s0
	v_cvt_pk_bf16_f32 v0, v0, s0
	global_store_short v[180:181], v48, off
	global_store_short v[180:181], v0, off offset:64
	s_and_saveexec_b64 s[0:1], s[2:3]
	s_cbranch_execz .LBB0_541
	v_lshlrev_b64 v[146:147], 7, v[102:103]
	v_lshl_add_u64 v[146:147], s[72:73], 0, v[146:147]
	s_waitcnt lgkmcnt(0)
	v_pk_add_f32 v[180:181], v[182:183], v[184:185]
	global_store_dwordx2 v[146:147], v[180:181], off
